# scan-loop-rewrite+prep-waves-setprio1+lean-chunk-setup
# speedup vs baseline: 1.0159x; 1.0159x over previous
; #define PREP_ROLE(jw, cc, slot) do { if (((jw) >> 1) == 0) prep_x(l, b, h, (jw) & 1, (cc), ring + (size_t)((slot) * 2 + ((jw) & 1)) * CHS * RSTEP, cst, lane); \
;                                      else prep_y(l, b, h, (jw) & 1, (cc), ring + (size_t)((slot) * 2 + ((jw) & 1)) * CHS * RSTEP, cst, lane); } while (0)
; __device__ __forceinline__ void yflush_issue(unsigned (&yo)[4], const bf16* yb2  , int dir, int cc, int lane) {
;     ...
;     if (cc >= NCH / 2) {
; #pragma unroll
;         for (int i = 0; i < 4; ++i) yo[i] = *(const unsigned*)(yb2 + (size_t)Y_T(dir, cc, 4 * i + rg) * DM);
; __device__ __forceinline__ void scan_phase(int l, LAS unsigned char* lds, int wave, int lane) {
;     ...
;         for (int c = 0; c < NCH; ++c) {
;             if (wave < 4) {
;                 scan_chunk(st, ring + (size_t)((c & 1) * 2 + dirw) * CHS * RSTEP, rhw, ybw + (c & 1) * CHS * 32, lane);
;             } else {
;                 unsigned yo[4];
;                 if (c > 0) yflush_issue(yo, yb2, dirw, c - 1, lane);
;                 if (c + 1 < NCH) PREP_ROLE(wave - 4, c + 1, (c + 1) & 1);
;                 if (c > 0) yflush_finish(yo, yb2, ybw + ((c - 1) & 1) * CHS * 32, dirw, c - 1, lane);
.LBB0_364:
	s_mov_b64 s[6:7], -1
	s_and_b64 vcc, exec, s[92:93]
	s_cbranch_vccz .LBB0_427
	s_setprio 1
	s_cmp_lg_u32 s81, 0
	v_mov_b64_e32 v[38:39], v[8:9]
	s_cselect_b64 s[78:79], -1, 0
	s_cmp_eq_u32 s81, 0
	v_mov_b64_e32 v[36:37], v[6:7]
	s_cbranch_scc1 .LBB0_370
	s_add_i32 s35, s81, -1
	s_cmp_gt_u32 s35, 63
	s_cbranch_scc1 .LBB0_368
	v_mov_b32_e32 v4, v3
	v_mov_b32_e32 v2, v3
	v_mov_b64_e32 v[38:39], v[4:5]
	s_mov_b64 s[6:7], 0
	v_mov_b64_e32 v[36:37], v[2:3]

; #define LAS __attribute__((address_space(3)))
; #define SCAN_LD_AV(AH0, AH1, P) do { const u32x2 q0 = *(const LAS u32x2*)((P) + 0), q1 = *(const LAS u32x2*)((P) + 8), q2 = *(const LAS u32x2*)((P) + 16), q3 = *(const LAS u32x2*)((P) + 24); \
;         AH0 = (u32x4){q0.x, q0.y, q1.x, q1.y}; AH1 = (u32x4){q2.x, q2.y, q3.x, q3.y}; } while (0)
; __device__ __forceinline__ void scan_chunk(f32x4 (&c)[4][2], const LAS float* sl  , int rh, LAS float* ybuf  , int lane) {
;     const int mg = lane >> 4, v16 = lane & 15;
;     const bool asel = (lane & 3) == 1;
;     const LAS float* vb = sl + 64 + 32 * rh + v16;
;     f32x4 wA[4], wB[4]; unsigned bkA[4], bkB[4];
;     u32x4 at = {0u, 0u, 0u, 0u}, bx0 = {0u, 0u, 0u, 0u}, bx1 = {0u, 0u, 0u, 0u};
;     float x0, x1;
;     {
;         u32x4 ah0, ah1; SCAN_LD_AV(ah0, ah1, sl + 192 + 2 * mg);
; #pragma unroll
;         for (int kt = 0; kt < 4; ++kt) { wA[kt] = *(const LAS f32x4*)(sl + 16 * kt + 4 * mg); bkA[kt] = ((const LAS unsigned*)sl)[128 + 16 * kt + v16]; }
;         f32x4 d0, d1; SCAN_DOTS(ah0, ah1, d0, d1);
;         x0 = asel ? d0[1] : d0[0]; x1 = asel ? d1[1] : d1[0];
;     }
;     float v0 = vb[0], v1 = vb[16];
.LBB0_427:
	s_and_b64 vcc, exec, s[6:7]
	s_cbranch_vccz .LBB0_434
	s_cmp_lg_u32 s81, 0
	s_cbranch_scc1 .Lscan_state_live
	v_and_b32_e32 v2, 63, v0
	v_lshrrev_b32_e32 v4, 6, v0
	s_nop 0
	v_readfirstlane_b32 s6, v4
	s_and_b32 s7, s6, 1
	s_mul_i32 s35, s7, 0x4100
	s_add_i32 s35, s35, 0x8000
	s_lshr_b32 s7, s6, 1
	s_and_b32 s7, s7, 1
	s_lshl_b32 s7, s7, 7
	s_lshl_b32 s6, s6, 12
	s_add_i32 s6, s6, 0x20800
	v_and_b32_e32 v4, 15, v2
	v_lshrrev_b32_e32 v5, 4, v2
	v_lshlrev_b32_e32 v27, 4, v5
	v_lshlrev_b32_e32 v28, 2, v4
	v_add_u32_e32 v29, s7, v28
	v_lshlrev_b32_e32 v31, 3, v5
	v_and_b32_e32 v10, 3, v2
	v_cmp_eq_u32_e64 s[48:49], 1, v10
	v_and_b32_e32 v11, 16, v2
	v_cmp_ne_u32_e64 s[50:51], 0, v11
	v_add_u32_e32 v11, 0x380, v31
	v_add_u32_e32 v26, 0x710, v31
	v_and_b32_e32 v10, 31, v2
	v_lshl_add_u32 v32, v10, 2, s6
	v_cndmask_b32_e64 v30, v11, v26, s[48:49]
	v_mov_b32_e32 v36, 0
	v_mov_b32_e32 v37, 0
	v_mov_b32_e32 v38, 0
	v_mov_b32_e32 v39, 0
	v_mov_b32_e32 v40, 0
	v_mov_b32_e32 v41, 0
	v_mov_b32_e32 v42, 0
	v_mov_b32_e32 v43, 0
	v_mov_b32_e32 v44, 0
	v_mov_b32_e32 v45, 0
	v_mov_b32_e32 v46, 0
	v_mov_b32_e32 v47, 0
	v_mov_b32_e32 v48, 0
	v_mov_b32_e32 v49, 0
	v_mov_b32_e32 v50, 0
	v_mov_b32_e32 v51, 0
	v_mov_b32_e32 v52, 0
	v_mov_b32_e32 v53, 0
	v_mov_b32_e32 v54, 0
	v_mov_b32_e32 v55, 0
	v_mov_b32_e32 v56, 0
	v_mov_b32_e32 v57, 0
	v_mov_b32_e32 v58, 0
	v_mov_b32_e32 v59, 0
	v_mov_b32_e32 v60, 0
	v_mov_b32_e32 v61, 0
	v_mov_b32_e32 v62, 0
	v_mov_b32_e32 v63, 0
	v_mov_b32_e32 v64, 0
	v_mov_b32_e32 v65, 0
	v_mov_b32_e32 v66, 0
	v_mov_b32_e32 v67, 0
	v_mov_b32_e32 v69, 0
	v_mov_b32_e32 v70, 0
	v_mov_b32_e32 v71, 0
	v_mov_b32_e32 v73, 0
	v_mov_b32_e32 v74, 0
	v_mov_b32_e32 v75, 0
	v_mov_b32_e32 v77, 0
	v_mov_b32_e32 v78, 0
	v_mov_b32_e32 v79, 0
	v_mov_b32_e32 v81, 0
	v_mov_b32_e32 v82, 0
	v_mov_b32_e32 v83, 0
	v_mov_b32_e32 v85, 0
	v_mov_b32_e32 v86, 0
	v_mov_b32_e32 v87, 0
	v_mov_b32_e32 v89, 0
	v_mov_b32_e32 v90, 0
	v_mov_b32_e32 v91, 0
	v_mov_b32_e32 v138, 0
	v_mov_b32_e32 v139, 0
	v_mov_b32_e32 v140, 0
	v_mov_b32_e32 v141, 0
	v_mov_b32_e32 v144, 0
	v_mov_b32_e32 v145, 0
	v_mov_b32_e32 v146, 0
	v_mov_b32_e32 v147, 0
	v_mov_b32_e32 v12, 0
	v_mov_b32_e32 v13, 0
	v_mov_b32_e32 v14, 0
	v_mov_b32_e32 v15, 0
	v_mov_b32_e32 v16, 0
	v_mov_b32_e32 v17, 0
	v_mov_b32_e32 v18, 0
	v_mov_b32_e32 v19, 0
.Lscan_state_live:
	s_and_b32 vcc_lo, s81, 1
	s_mul_i32 vcc_hi, vcc_lo, 0x8200
	s_add_i32 s52, s35, vcc_hi
	s_lshl_b32 vcc_lo, vcc_lo, 11
	v_add_u32_e32 v10, s52, v31
	v_add_u32_e32 v22, s52, v27
	v_add_u32_e32 v23, s52, v28
	v_add_u32_e32 v24, s52, v29
	ds_read2_b64 v[108:111], v10 offset0:96 offset1:100
	ds_read2_b64 v[112:115], v10 offset0:104 offset1:108
	ds_read_b128 v[92:95], v22 offset:0
	ds_read_b128 v[96:99], v22 offset:64
	ds_read_b128 v[100:103], v22 offset:128
	ds_read_b128 v[104:107], v22 offset:192
	ds_read_b32 v68, v23 offset:512
	ds_read_b32 v72, v23 offset:576
	ds_read_b32 v76, v23 offset:640
	ds_read_b32 v80, v23 offset:704
	ds_read_b32 v116, v24 offset:256
	ds_read_b32 v117, v24 offset:320
	v_add_u32_e32 v21, s52, v30
	v_add_u32_e32 v25, vcc_lo, v32
	s_waitcnt lgkmcnt(11)
	v_mfma_f32_16x16x32_bf16 v[130:133], v[108:111], v[138:141], 0
	v_mfma_f32_16x16x32_bf16 v[134:137], v[108:111], v[144:147], 0
	s_waitcnt lgkmcnt(10)
	v_mfma_f32_16x16x32_bf16 v[130:133], v[112:115], v[12:15], v[130:133]
	s_waitcnt lgkmcnt(9)
	v_mul_f32_e32 v36, v36, v92
	v_mul_f32_e32 v37, v37, v93
	v_mfma_f32_16x16x32_bf16 v[134:137], v[112:115], v[16:19], v[134:137]
	v_mul_f32_e32 v38, v38, v94
	v_mul_f32_e32 v39, v39, v95
	v_mul_f32_e32 v40, v40, v92
	v_mul_f32_e32 v41, v41, v93
	v_mul_f32_e32 v42, v42, v94
	v_mul_f32_e32 v43, v43, v95
	s_waitcnt lgkmcnt(1)
	v_cvt_pk_bf16_f32 v84, v131, v116
	v_mul_f32_e32 v44, v44, v96
	s_waitcnt lgkmcnt(0)
	v_cvt_pk_bf16_f32 v88, v135, v117
	v_mul_f32_e32 v45, v45, v97
	v_mfma_f32_16x16x32_bf16 v[36:39], v[68:71], v[84:87], v[36:39]
	v_mul_f32_e32 v46, v46, v98
	v_mul_f32_e32 v47, v47, v99
	ds_read2_b64 v[108:111], v21 offset0:0 offset1:4
	v_mfma_f32_16x16x32_bf16 v[40:43], v[68:71], v[88:91], v[40:43]
	v_mul_f32_e32 v48, v48, v96
	v_mul_f32_e32 v49, v49, v97
	v_mul_f32_e32 v50, v50, v98
	v_mul_f32_e32 v51, v51, v99
	ds_read_b32 v68, v23 offset:1552
	v_mfma_f32_16x16x32_bf16 v[44:47], v[72:75], v[84:87], v[44:47]
	v_mul_f32_e32 v52, v52, v100
	v_mul_f32_e32 v53, v53, v101
	v_mul_f32_e32 v54, v54, v102
	v_mul_f32_e32 v55, v55, v103
	ds_read2_b64 v[112:115], v21 offset0:8 offset1:12
	v_mfma_f32_16x16x32_bf16 v[48:51], v[72:75], v[88:91], v[48:51]
	v_mul_f32_e32 v56, v56, v100
	v_mul_f32_e32 v57, v57, v101
	v_mul_f32_e32 v58, v58, v102
	v_mul_f32_e32 v59, v59, v103
	ds_read_b32 v72, v23 offset:1616
	v_mfma_f32_16x16x32_bf16 v[52:55], v[76:79], v[84:87], v[52:55]
	v_mul_f32_e32 v60, v60, v104
	v_mul_f32_e32 v61, v61, v105
	v_mul_f32_e32 v62, v62, v106
	v_mul_f32_e32 v63, v63, v107
	ds_read_b32 v116, v24 offset:1296
	v_mfma_f32_16x16x32_bf16 v[56:59], v[76:79], v[88:91], v[56:59]
	v_mul_f32_e32 v64, v64, v104
	v_mul_f32_e32 v65, v65, v105
	v_mul_f32_e32 v66, v66, v106
	v_mul_f32_e32 v67, v67, v107
	ds_read_b32 v76, v23 offset:1680
	v_mfma_f32_16x16x32_bf16 v[60:63], v[80:83], v[84:87], v[60:63]
	ds_read_b32 v117, v24 offset:1360
	ds_read_b128 v[92:95], v22 offset:1040
	v_mfma_f32_16x16x32_bf16 v[64:67], v[80:83], v[88:91], v[64:67]
	ds_read_b32 v80, v23 offset:1744
	ds_read_b128 v[96:99], v22 offset:1104
	v_cvt_pk_bf16_f32 v138, v36, v37
	v_cvt_pk_bf16_f32 v139, v38, v39
	v_cvt_pk_bf16_f32 v140, v44, v45
	v_cvt_pk_bf16_f32 v141, v46, v47
	ds_read_b128 v[100:103], v22 offset:1168
	v_cvt_pk_bf16_f32 v144, v40, v41
	v_cvt_pk_bf16_f32 v145, v42, v43
	s_waitcnt lgkmcnt(10)
	v_mfma_f32_16x16x32_bf16 v[130:133], v[108:111], v[138:141], 0
	v_cvt_pk_bf16_f32 v146, v48, v49
	v_cvt_pk_bf16_f32 v147, v50, v51
	ds_read_b128 v[104:107], v22 offset:1232
	v_cvt_pk_bf16_f32 v12, v52, v53
	v_cvt_pk_bf16_f32 v13, v54, v55
	v_mfma_f32_16x16x32_bf16 v[134:137], v[108:111], v[144:147], 0
	v_cvt_pk_bf16_f32 v14, v60, v61
	v_cvt_pk_bf16_f32 v15, v62, v63
	v_cvt_pk_bf16_f32 v16, v56, v57
	v_cvt_pk_bf16_f32 v17, v58, v59
	s_waitcnt lgkmcnt(9)
	v_mfma_f32_16x16x32_bf16 v[130:133], v[112:115], v[12:15], v[130:133]
	v_cvt_pk_bf16_f32 v18, v64, v65
	v_cvt_pk_bf16_f32 v19, v66, v67
	s_waitcnt lgkmcnt(4)
	v_mul_f32_e32 v36, v36, v92
	v_mul_f32_e32 v37, v37, v93
	v_mfma_f32_16x16x32_bf16 v[134:137], v[112:115], v[16:19], v[134:137]
	v_mul_f32_e32 v38, v38, v94
	v_mul_f32_e32 v39, v39, v95
	v_mul_f32_e32 v40, v40, v92
	v_mul_f32_e32 v41, v41, v93
	v_mul_f32_e32 v42, v42, v94
	v_mul_f32_e32 v43, v43, v95
	v_cvt_pk_bf16_f32 v84, v131, v116
	s_waitcnt lgkmcnt(2)
	v_mul_f32_e32 v44, v44, v96
	v_cvt_pk_bf16_f32 v88, v135, v117
	v_cndmask_b32_e64 v20, v130, v134, s[50:51]
	ds_write_b32 v25, v20 offset:0
	v_mfma_f32_16x16x32_bf16 v[36:39], v[68:71], v[84:87], v[36:39]
	v_mul_f32_e32 v45, v45, v97
	v_mul_f32_e32 v46, v46, v98
	v_mul_f32_e32 v47, v47, v99
	ds_read2_b64 v[108:111], v21 offset0:130 offset1:134
	v_mfma_f32_16x16x32_bf16 v[40:43], v[68:71], v[88:91], v[40:43]
	v_mul_f32_e32 v48, v48, v96
	v_mul_f32_e32 v49, v49, v97
	v_mul_f32_e32 v50, v50, v98
	v_mul_f32_e32 v51, v51, v99
	ds_read_b32 v68, v23 offset:2592
	v_mfma_f32_16x16x32_bf16 v[44:47], v[72:75], v[84:87], v[44:47]
	s_waitcnt lgkmcnt(4)
	v_mul_f32_e32 v52, v52, v100
	v_mul_f32_e32 v53, v53, v101
	v_mul_f32_e32 v54, v54, v102
	v_mul_f32_e32 v55, v55, v103
	ds_read2_b64 v[112:115], v21 offset0:138 offset1:142
	v_mfma_f32_16x16x32_bf16 v[48:51], v[72:75], v[88:91], v[48:51]
	v_mul_f32_e32 v56, v56, v100
	v_mul_f32_e32 v57, v57, v101
	v_mul_f32_e32 v58, v58, v102
	v_mul_f32_e32 v59, v59, v103
	ds_read_b32 v72, v23 offset:2656
	v_mfma_f32_16x16x32_bf16 v[52:55], v[76:79], v[84:87], v[52:55]
	s_waitcnt lgkmcnt(5)
	v_mul_f32_e32 v60, v60, v104
	v_mul_f32_e32 v61, v61, v105
	v_mul_f32_e32 v62, v62, v106
	v_mul_f32_e32 v63, v63, v107
	ds_read_b32 v116, v24 offset:2336
	v_mfma_f32_16x16x32_bf16 v[56:59], v[76:79], v[88:91], v[56:59]
	v_mul_f32_e32 v64, v64, v104
	v_mul_f32_e32 v65, v65, v105
	v_mul_f32_e32 v66, v66, v106
	v_mul_f32_e32 v67, v67, v107
	ds_read_b32 v76, v23 offset:2720
	v_mfma_f32_16x16x32_bf16 v[60:63], v[80:83], v[84:87], v[60:63]
	ds_read_b32 v117, v24 offset:2400
	ds_read_b128 v[92:95], v22 offset:2080
	v_add_u32_e32 v21, 0x820, v21
	v_mfma_f32_16x16x32_bf16 v[64:67], v[80:83], v[88:91], v[64:67]
	ds_read_b32 v80, v23 offset:2784
	ds_read_b128 v[96:99], v22 offset:2144
	v_cvt_pk_bf16_f32 v138, v36, v37
	v_cvt_pk_bf16_f32 v139, v38, v39
	v_cvt_pk_bf16_f32 v140, v44, v45
	v_cvt_pk_bf16_f32 v141, v46, v47
	ds_read_b128 v[100:103], v22 offset:2208
	v_cvt_pk_bf16_f32 v144, v40, v41
	v_cvt_pk_bf16_f32 v145, v42, v43
	s_waitcnt lgkmcnt(10)
	v_mfma_f32_16x16x32_bf16 v[130:133], v[108:111], v[138:141], 0
	v_cvt_pk_bf16_f32 v146, v48, v49
	v_cvt_pk_bf16_f32 v147, v50, v51
	ds_read_b128 v[104:107], v22 offset:2272
	v_cvt_pk_bf16_f32 v12, v52, v53
	v_cvt_pk_bf16_f32 v13, v54, v55
	v_mfma_f32_16x16x32_bf16 v[134:137], v[108:111], v[144:147], 0
	v_cvt_pk_bf16_f32 v14, v60, v61
	v_cvt_pk_bf16_f32 v15, v62, v63
	v_cvt_pk_bf16_f32 v16, v56, v57
	v_cvt_pk_bf16_f32 v17, v58, v59
	s_waitcnt lgkmcnt(9)
	v_mfma_f32_16x16x32_bf16 v[130:133], v[112:115], v[12:15], v[130:133]
	v_cvt_pk_bf16_f32 v18, v64, v65
	v_cvt_pk_bf16_f32 v19, v66, v67
	s_waitcnt lgkmcnt(4)
	v_mul_f32_e32 v36, v36, v92
	v_mul_f32_e32 v37, v37, v93
	v_mfma_f32_16x16x32_bf16 v[134:137], v[112:115], v[16:19], v[134:137]
	v_mul_f32_e32 v38, v38, v94
	v_mul_f32_e32 v39, v39, v95
	v_mul_f32_e32 v40, v40, v92
	v_mul_f32_e32 v41, v41, v93
	v_mul_f32_e32 v42, v42, v94
	v_mul_f32_e32 v43, v43, v95
	v_cvt_pk_bf16_f32 v84, v131, v116
	s_waitcnt lgkmcnt(2)
	v_mul_f32_e32 v44, v44, v96
	v_cvt_pk_bf16_f32 v88, v135, v117
	v_cndmask_b32_e64 v20, v130, v134, s[50:51]
	ds_write_b32 v25, v20 offset:128
	v_mfma_f32_16x16x32_bf16 v[36:39], v[68:71], v[84:87], v[36:39]
	v_mul_f32_e32 v45, v45, v97
	v_mul_f32_e32 v46, v46, v98
	v_mul_f32_e32 v47, v47, v99
	ds_read2_b64 v[108:111], v21 offset0:0 offset1:4
	v_mfma_f32_16x16x32_bf16 v[40:43], v[68:71], v[88:91], v[40:43]
	v_mul_f32_e32 v48, v48, v96
	v_mul_f32_e32 v49, v49, v97
	v_mul_f32_e32 v50, v50, v98
	v_mul_f32_e32 v51, v51, v99
	ds_read_b32 v68, v23 offset:3632
	v_mfma_f32_16x16x32_bf16 v[44:47], v[72:75], v[84:87], v[44:47]
	s_waitcnt lgkmcnt(4)
	v_mul_f32_e32 v52, v52, v100
	v_mul_f32_e32 v53, v53, v101
	v_mul_f32_e32 v54, v54, v102
	v_mul_f32_e32 v55, v55, v103
	ds_read2_b64 v[112:115], v21 offset0:8 offset1:12
	v_mfma_f32_16x16x32_bf16 v[48:51], v[72:75], v[88:91], v[48:51]
	v_mul_f32_e32 v56, v56, v100
	v_mul_f32_e32 v57, v57, v101
	v_mul_f32_e32 v58, v58, v102
	v_mul_f32_e32 v59, v59, v103
	ds_read_b32 v72, v23 offset:3696
	v_mfma_f32_16x16x32_bf16 v[52:55], v[76:79], v[84:87], v[52:55]
	s_waitcnt lgkmcnt(5)
	v_mul_f32_e32 v60, v60, v104
	v_mul_f32_e32 v61, v61, v105
	v_mul_f32_e32 v62, v62, v106
	v_mul_f32_e32 v63, v63, v107
	ds_read_b32 v116, v24 offset:3376
	v_mfma_f32_16x16x32_bf16 v[56:59], v[76:79], v[88:91], v[56:59]
	v_mul_f32_e32 v64, v64, v104
	v_mul_f32_e32 v65, v65, v105
	v_mul_f32_e32 v66, v66, v106
	v_mul_f32_e32 v67, v67, v107
	ds_read_b32 v76, v23 offset:3760
	v_mfma_f32_16x16x32_bf16 v[60:63], v[80:83], v[84:87], v[60:63]
	ds_read_b32 v117, v24 offset:3440
	ds_read_b128 v[92:95], v22 offset:3120
	v_mfma_f32_16x16x32_bf16 v[64:67], v[80:83], v[88:91], v[64:67]
	ds_read_b32 v80, v23 offset:3824
	ds_read_b128 v[96:99], v22 offset:3184
	v_cvt_pk_bf16_f32 v138, v36, v37
	v_cvt_pk_bf16_f32 v139, v38, v39
	v_cvt_pk_bf16_f32 v140, v44, v45
	v_cvt_pk_bf16_f32 v141, v46, v47
	ds_read_b128 v[100:103], v22 offset:3248
	v_cvt_pk_bf16_f32 v144, v40, v41
	v_cvt_pk_bf16_f32 v145, v42, v43
	s_waitcnt lgkmcnt(10)
	v_mfma_f32_16x16x32_bf16 v[130:133], v[108:111], v[138:141], 0
	v_cvt_pk_bf16_f32 v146, v48, v49
	v_cvt_pk_bf16_f32 v147, v50, v51
	ds_read_b128 v[104:107], v22 offset:3312
	v_cvt_pk_bf16_f32 v12, v52, v53
	v_cvt_pk_bf16_f32 v13, v54, v55
	v_mfma_f32_16x16x32_bf16 v[134:137], v[108:111], v[144:147], 0
	v_cvt_pk_bf16_f32 v14, v60, v61
	v_cvt_pk_bf16_f32 v15, v62, v63
	v_cvt_pk_bf16_f32 v16, v56, v57
	v_cvt_pk_bf16_f32 v17, v58, v59
	s_waitcnt lgkmcnt(9)
	v_mfma_f32_16x16x32_bf16 v[130:133], v[112:115], v[12:15], v[130:133]
	v_cvt_pk_bf16_f32 v18, v64, v65
	v_cvt_pk_bf16_f32 v19, v66, v67
	s_waitcnt lgkmcnt(4)
	v_mul_f32_e32 v36, v36, v92
	v_mul_f32_e32 v37, v37, v93
	v_mfma_f32_16x16x32_bf16 v[134:137], v[112:115], v[16:19], v[134:137]
	v_mul_f32_e32 v38, v38, v94
	v_mul_f32_e32 v39, v39, v95
	v_mul_f32_e32 v40, v40, v92
	v_mul_f32_e32 v41, v41, v93
	v_mul_f32_e32 v42, v42, v94
	v_mul_f32_e32 v43, v43, v95
	v_cvt_pk_bf16_f32 v84, v131, v116
	s_waitcnt lgkmcnt(2)
	v_mul_f32_e32 v44, v44, v96
	v_cvt_pk_bf16_f32 v88, v135, v117
	v_cndmask_b32_e64 v20, v130, v134, s[50:51]
	ds_write_b32 v25, v20 offset:256
	v_mfma_f32_16x16x32_bf16 v[36:39], v[68:71], v[84:87], v[36:39]
	v_mul_f32_e32 v45, v45, v97
	v_mul_f32_e32 v46, v46, v98
	v_mul_f32_e32 v47, v47, v99
	ds_read2_b64 v[108:111], v21 offset0:130 offset1:134
	v_mfma_f32_16x16x32_bf16 v[40:43], v[68:71], v[88:91], v[40:43]
	v_mul_f32_e32 v48, v48, v96
	v_mul_f32_e32 v49, v49, v97
	v_mul_f32_e32 v50, v50, v98
	v_mul_f32_e32 v51, v51, v99
	ds_read_b32 v68, v23 offset:4672
	v_mfma_f32_16x16x32_bf16 v[44:47], v[72:75], v[84:87], v[44:47]
	s_waitcnt lgkmcnt(4)
	v_mul_f32_e32 v52, v52, v100
	v_mul_f32_e32 v53, v53, v101
	v_mul_f32_e32 v54, v54, v102
	v_mul_f32_e32 v55, v55, v103
	ds_read2_b64 v[112:115], v21 offset0:138 offset1:142
	v_mfma_f32_16x16x32_bf16 v[48:51], v[72:75], v[88:91], v[48:51]
	v_mul_f32_e32 v56, v56, v100
	v_mul_f32_e32 v57, v57, v101
	v_mul_f32_e32 v58, v58, v102
	v_mul_f32_e32 v59, v59, v103
	ds_read_b32 v72, v23 offset:4736
	v_mfma_f32_16x16x32_bf16 v[52:55], v[76:79], v[84:87], v[52:55]
	s_waitcnt lgkmcnt(5)
	v_mul_f32_e32 v60, v60, v104
	v_mul_f32_e32 v61, v61, v105
	v_mul_f32_e32 v62, v62, v106
	v_mul_f32_e32 v63, v63, v107
	ds_read_b32 v116, v24 offset:4416
	v_mfma_f32_16x16x32_bf16 v[56:59], v[76:79], v[88:91], v[56:59]
	v_mul_f32_e32 v64, v64, v104
	v_mul_f32_e32 v65, v65, v105
	v_mul_f32_e32 v66, v66, v106
	v_mul_f32_e32 v67, v67, v107
	ds_read_b32 v76, v23 offset:4800
	v_mfma_f32_16x16x32_bf16 v[60:63], v[80:83], v[84:87], v[60:63]
	ds_read_b32 v117, v24 offset:4480
	ds_read_b128 v[92:95], v22 offset:4160
	v_add_u32_e32 v21, 0x820, v21
	v_mfma_f32_16x16x32_bf16 v[64:67], v[80:83], v[88:91], v[64:67]
	ds_read_b32 v80, v23 offset:4864
	ds_read_b128 v[96:99], v22 offset:4224
	v_cvt_pk_bf16_f32 v138, v36, v37
	v_cvt_pk_bf16_f32 v139, v38, v39
	v_cvt_pk_bf16_f32 v140, v44, v45
	v_cvt_pk_bf16_f32 v141, v46, v47
	ds_read_b128 v[100:103], v22 offset:4288
	v_cvt_pk_bf16_f32 v144, v40, v41
	v_cvt_pk_bf16_f32 v145, v42, v43
	s_waitcnt lgkmcnt(10)
	v_mfma_f32_16x16x32_bf16 v[130:133], v[108:111], v[138:141], 0
	v_cvt_pk_bf16_f32 v146, v48, v49
	v_cvt_pk_bf16_f32 v147, v50, v51
	ds_read_b128 v[104:107], v22 offset:4352
	v_cvt_pk_bf16_f32 v12, v52, v53
	v_cvt_pk_bf16_f32 v13, v54, v55
	v_mfma_f32_16x16x32_bf16 v[134:137], v[108:111], v[144:147], 0
	v_cvt_pk_bf16_f32 v14, v60, v61
	v_cvt_pk_bf16_f32 v15, v62, v63
	v_cvt_pk_bf16_f32 v16, v56, v57
	v_cvt_pk_bf16_f32 v17, v58, v59
	s_waitcnt lgkmcnt(9)
	v_mfma_f32_16x16x32_bf16 v[130:133], v[112:115], v[12:15], v[130:133]
	v_cvt_pk_bf16_f32 v18, v64, v65
	v_cvt_pk_bf16_f32 v19, v66, v67
	s_waitcnt lgkmcnt(4)
	v_mul_f32_e32 v36, v36, v92
	v_mul_f32_e32 v37, v37, v93
	v_mfma_f32_16x16x32_bf16 v[134:137], v[112:115], v[16:19], v[134:137]
	v_mul_f32_e32 v38, v38, v94
	v_mul_f32_e32 v39, v39, v95
	v_mul_f32_e32 v40, v40, v92
	v_mul_f32_e32 v41, v41, v93
	v_mul_f32_e32 v42, v42, v94
	v_mul_f32_e32 v43, v43, v95
	v_cvt_pk_bf16_f32 v84, v131, v116
	s_waitcnt lgkmcnt(2)
	v_mul_f32_e32 v44, v44, v96
	v_cvt_pk_bf16_f32 v88, v135, v117
	v_cndmask_b32_e64 v20, v130, v134, s[50:51]
	ds_write_b32 v25, v20 offset:384
	v_mfma_f32_16x16x32_bf16 v[36:39], v[68:71], v[84:87], v[36:39]
	v_mul_f32_e32 v45, v45, v97
	v_mul_f32_e32 v46, v46, v98
	v_mul_f32_e32 v47, v47, v99
	ds_read2_b64 v[108:111], v21 offset0:0 offset1:4
	v_mfma_f32_16x16x32_bf16 v[40:43], v[68:71], v[88:91], v[40:43]
	v_mul_f32_e32 v48, v48, v96
	v_mul_f32_e32 v49, v49, v97
	v_mul_f32_e32 v50, v50, v98
	v_mul_f32_e32 v51, v51, v99
	ds_read_b32 v68, v23 offset:5712
	v_mfma_f32_16x16x32_bf16 v[44:47], v[72:75], v[84:87], v[44:47]
	s_waitcnt lgkmcnt(4)
	v_mul_f32_e32 v52, v52, v100
	v_mul_f32_e32 v53, v53, v101
	v_mul_f32_e32 v54, v54, v102
	v_mul_f32_e32 v55, v55, v103
	ds_read2_b64 v[112:115], v21 offset0:8 offset1:12
	v_mfma_f32_16x16x32_bf16 v[48:51], v[72:75], v[88:91], v[48:51]
	v_mul_f32_e32 v56, v56, v100
	v_mul_f32_e32 v57, v57, v101
	v_mul_f32_e32 v58, v58, v102
	v_mul_f32_e32 v59, v59, v103
	ds_read_b32 v72, v23 offset:5776
	v_mfma_f32_16x16x32_bf16 v[52:55], v[76:79], v[84:87], v[52:55]
	s_waitcnt lgkmcnt(5)
	v_mul_f32_e32 v60, v60, v104
	v_mul_f32_e32 v61, v61, v105
	v_mul_f32_e32 v62, v62, v106
	v_mul_f32_e32 v63, v63, v107
	ds_read_b32 v116, v24 offset:5456
	v_mfma_f32_16x16x32_bf16 v[56:59], v[76:79], v[88:91], v[56:59]
	v_mul_f32_e32 v64, v64, v104
	v_mul_f32_e32 v65, v65, v105
	v_mul_f32_e32 v66, v66, v106
	v_mul_f32_e32 v67, v67, v107
	ds_read_b32 v76, v23 offset:5840
	v_mfma_f32_16x16x32_bf16 v[60:63], v[80:83], v[84:87], v[60:63]
	ds_read_b32 v117, v24 offset:5520
	ds_read_b128 v[92:95], v22 offset:5200
	v_mfma_f32_16x16x32_bf16 v[64:67], v[80:83], v[88:91], v[64:67]
	ds_read_b32 v80, v23 offset:5904
	ds_read_b128 v[96:99], v22 offset:5264
	v_cvt_pk_bf16_f32 v138, v36, v37
	v_cvt_pk_bf16_f32 v139, v38, v39
	v_cvt_pk_bf16_f32 v140, v44, v45
	v_cvt_pk_bf16_f32 v141, v46, v47
	ds_read_b128 v[100:103], v22 offset:5328
	v_cvt_pk_bf16_f32 v144, v40, v41
	v_cvt_pk_bf16_f32 v145, v42, v43
	s_waitcnt lgkmcnt(10)
	v_mfma_f32_16x16x32_bf16 v[130:133], v[108:111], v[138:141], 0
	v_cvt_pk_bf16_f32 v146, v48, v49
	v_cvt_pk_bf16_f32 v147, v50, v51
	ds_read_b128 v[104:107], v22 offset:5392
	v_cvt_pk_bf16_f32 v12, v52, v53
	v_cvt_pk_bf16_f32 v13, v54, v55
	v_mfma_f32_16x16x32_bf16 v[134:137], v[108:111], v[144:147], 0
	v_cvt_pk_bf16_f32 v14, v60, v61
	v_cvt_pk_bf16_f32 v15, v62, v63
	v_cvt_pk_bf16_f32 v16, v56, v57
	v_cvt_pk_bf16_f32 v17, v58, v59
	s_waitcnt lgkmcnt(9)
	v_mfma_f32_16x16x32_bf16 v[130:133], v[112:115], v[12:15], v[130:133]
	v_cvt_pk_bf16_f32 v18, v64, v65
	v_cvt_pk_bf16_f32 v19, v66, v67
	s_waitcnt lgkmcnt(4)
	v_mul_f32_e32 v36, v36, v92
	v_mul_f32_e32 v37, v37, v93
	v_mfma_f32_16x16x32_bf16 v[134:137], v[112:115], v[16:19], v[134:137]
	v_mul_f32_e32 v38, v38, v94
	v_mul_f32_e32 v39, v39, v95
	v_mul_f32_e32 v40, v40, v92
	v_mul_f32_e32 v41, v41, v93
	v_mul_f32_e32 v42, v42, v94
	v_mul_f32_e32 v43, v43, v95
	v_cvt_pk_bf16_f32 v84, v131, v116
	s_waitcnt lgkmcnt(2)
	v_mul_f32_e32 v44, v44, v96
	v_cvt_pk_bf16_f32 v88, v135, v117
	v_cndmask_b32_e64 v20, v130, v134, s[50:51]
	ds_write_b32 v25, v20 offset:512
	v_mfma_f32_16x16x32_bf16 v[36:39], v[68:71], v[84:87], v[36:39]
	v_mul_f32_e32 v45, v45, v97
	v_mul_f32_e32 v46, v46, v98
	v_mul_f32_e32 v47, v47, v99
	ds_read2_b64 v[108:111], v21 offset0:130 offset1:134
	v_mfma_f32_16x16x32_bf16 v[40:43], v[68:71], v[88:91], v[40:43]
	v_mul_f32_e32 v48, v48, v96
	v_mul_f32_e32 v49, v49, v97
	v_mul_f32_e32 v50, v50, v98
	v_mul_f32_e32 v51, v51, v99
	ds_read_b32 v68, v23 offset:6752
	v_mfma_f32_16x16x32_bf16 v[44:47], v[72:75], v[84:87], v[44:47]
	s_waitcnt lgkmcnt(4)
	v_mul_f32_e32 v52, v52, v100
	v_mul_f32_e32 v53, v53, v101
	v_mul_f32_e32 v54, v54, v102
	v_mul_f32_e32 v55, v55, v103
	ds_read2_b64 v[112:115], v21 offset0:138 offset1:142
	v_mfma_f32_16x16x32_bf16 v[48:51], v[72:75], v[88:91], v[48:51]
	v_mul_f32_e32 v56, v56, v100
	v_mul_f32_e32 v57, v57, v101
	v_mul_f32_e32 v58, v58, v102
	v_mul_f32_e32 v59, v59, v103
	ds_read_b32 v72, v23 offset:6816
	v_mfma_f32_16x16x32_bf16 v[52:55], v[76:79], v[84:87], v[52:55]
	s_waitcnt lgkmcnt(5)
	v_mul_f32_e32 v60, v60, v104
	v_mul_f32_e32 v61, v61, v105
	v_mul_f32_e32 v62, v62, v106
	v_mul_f32_e32 v63, v63, v107
	ds_read_b32 v116, v24 offset:6496
	v_mfma_f32_16x16x32_bf16 v[56:59], v[76:79], v[88:91], v[56:59]
	v_mul_f32_e32 v64, v64, v104
	v_mul_f32_e32 v65, v65, v105
	v_mul_f32_e32 v66, v66, v106
	v_mul_f32_e32 v67, v67, v107
	ds_read_b32 v76, v23 offset:6880
	v_mfma_f32_16x16x32_bf16 v[60:63], v[80:83], v[84:87], v[60:63]
	ds_read_b32 v117, v24 offset:6560
	ds_read_b128 v[92:95], v22 offset:6240
	v_add_u32_e32 v21, 0x820, v21
	v_mfma_f32_16x16x32_bf16 v[64:67], v[80:83], v[88:91], v[64:67]
	ds_read_b32 v80, v23 offset:6944
	ds_read_b128 v[96:99], v22 offset:6304
	v_cvt_pk_bf16_f32 v138, v36, v37
	v_cvt_pk_bf16_f32 v139, v38, v39
	v_cvt_pk_bf16_f32 v140, v44, v45
	v_cvt_pk_bf16_f32 v141, v46, v47
	ds_read_b128 v[100:103], v22 offset:6368
	v_cvt_pk_bf16_f32 v144, v40, v41
	v_cvt_pk_bf16_f32 v145, v42, v43
	s_waitcnt lgkmcnt(10)
	v_mfma_f32_16x16x32_bf16 v[130:133], v[108:111], v[138:141], 0
	v_cvt_pk_bf16_f32 v146, v48, v49
	v_cvt_pk_bf16_f32 v147, v50, v51
	ds_read_b128 v[104:107], v22 offset:6432
	v_cvt_pk_bf16_f32 v12, v52, v53
	v_cvt_pk_bf16_f32 v13, v54, v55
	v_mfma_f32_16x16x32_bf16 v[134:137], v[108:111], v[144:147], 0
	v_cvt_pk_bf16_f32 v14, v60, v61
	v_cvt_pk_bf16_f32 v15, v62, v63
	v_cvt_pk_bf16_f32 v16, v56, v57
	v_cvt_pk_bf16_f32 v17, v58, v59
	s_waitcnt lgkmcnt(9)
	v_mfma_f32_16x16x32_bf16 v[130:133], v[112:115], v[12:15], v[130:133]
	v_cvt_pk_bf16_f32 v18, v64, v65
	v_cvt_pk_bf16_f32 v19, v66, v67
	s_waitcnt lgkmcnt(4)
	v_mul_f32_e32 v36, v36, v92
	v_mul_f32_e32 v37, v37, v93
	v_mfma_f32_16x16x32_bf16 v[134:137], v[112:115], v[16:19], v[134:137]
	v_mul_f32_e32 v38, v38, v94
	v_mul_f32_e32 v39, v39, v95
	v_mul_f32_e32 v40, v40, v92
	v_mul_f32_e32 v41, v41, v93
	v_mul_f32_e32 v42, v42, v94
	v_mul_f32_e32 v43, v43, v95
	v_cvt_pk_bf16_f32 v84, v131, v116
	s_waitcnt lgkmcnt(2)
	v_mul_f32_e32 v44, v44, v96
	v_cvt_pk_bf16_f32 v88, v135, v117
	v_cndmask_b32_e64 v20, v130, v134, s[50:51]
	ds_write_b32 v25, v20 offset:640
	v_mfma_f32_16x16x32_bf16 v[36:39], v[68:71], v[84:87], v[36:39]
	v_mul_f32_e32 v45, v45, v97
	v_mul_f32_e32 v46, v46, v98
	v_mul_f32_e32 v47, v47, v99
	ds_read2_b64 v[108:111], v21 offset0:0 offset1:4
	v_mfma_f32_16x16x32_bf16 v[40:43], v[68:71], v[88:91], v[40:43]
	v_mul_f32_e32 v48, v48, v96
	v_mul_f32_e32 v49, v49, v97
	v_mul_f32_e32 v50, v50, v98
	v_mul_f32_e32 v51, v51, v99
	ds_read_b32 v68, v23 offset:7792
	v_mfma_f32_16x16x32_bf16 v[44:47], v[72:75], v[84:87], v[44:47]
	s_waitcnt lgkmcnt(4)
	v_mul_f32_e32 v52, v52, v100
	v_mul_f32_e32 v53, v53, v101
	v_mul_f32_e32 v54, v54, v102
	v_mul_f32_e32 v55, v55, v103
	ds_read2_b64 v[112:115], v21 offset0:8 offset1:12
	v_mfma_f32_16x16x32_bf16 v[48:51], v[72:75], v[88:91], v[48:51]
	v_mul_f32_e32 v56, v56, v100
	v_mul_f32_e32 v57, v57, v101
	v_mul_f32_e32 v58, v58, v102
	v_mul_f32_e32 v59, v59, v103
	ds_read_b32 v72, v23 offset:7856
	v_mfma_f32_16x16x32_bf16 v[52:55], v[76:79], v[84:87], v[52:55]
	s_waitcnt lgkmcnt(5)
	v_mul_f32_e32 v60, v60, v104
	v_mul_f32_e32 v61, v61, v105
	v_mul_f32_e32 v62, v62, v106
	v_mul_f32_e32 v63, v63, v107
	ds_read_b32 v116, v24 offset:7536
	v_mfma_f32_16x16x32_bf16 v[56:59], v[76:79], v[88:91], v[56:59]
	v_mul_f32_e32 v64, v64, v104
	v_mul_f32_e32 v65, v65, v105
	v_mul_f32_e32 v66, v66, v106
	v_mul_f32_e32 v67, v67, v107
	ds_read_b32 v76, v23 offset:7920
	v_mfma_f32_16x16x32_bf16 v[60:63], v[80:83], v[84:87], v[60:63]
	ds_read_b32 v117, v24 offset:7600
	ds_read_b128 v[92:95], v22 offset:7280
	v_mfma_f32_16x16x32_bf16 v[64:67], v[80:83], v[88:91], v[64:67]
	ds_read_b32 v80, v23 offset:7984
	ds_read_b128 v[96:99], v22 offset:7344
	v_cvt_pk_bf16_f32 v138, v36, v37
	v_cvt_pk_bf16_f32 v139, v38, v39
	v_cvt_pk_bf16_f32 v140, v44, v45
	v_cvt_pk_bf16_f32 v141, v46, v47
	ds_read_b128 v[100:103], v22 offset:7408
	v_cvt_pk_bf16_f32 v144, v40, v41
	v_cvt_pk_bf16_f32 v145, v42, v43
	s_waitcnt lgkmcnt(10)
	v_mfma_f32_16x16x32_bf16 v[130:133], v[108:111], v[138:141], 0
	v_cvt_pk_bf16_f32 v146, v48, v49
	v_cvt_pk_bf16_f32 v147, v50, v51
	ds_read_b128 v[104:107], v22 offset:7472
	v_cvt_pk_bf16_f32 v12, v52, v53
	v_cvt_pk_bf16_f32 v13, v54, v55
	v_mfma_f32_16x16x32_bf16 v[134:137], v[108:111], v[144:147], 0
	v_cvt_pk_bf16_f32 v14, v60, v61
	v_cvt_pk_bf16_f32 v15, v62, v63
	v_cvt_pk_bf16_f32 v16, v56, v57
	v_cvt_pk_bf16_f32 v17, v58, v59
	s_waitcnt lgkmcnt(9)
	v_mfma_f32_16x16x32_bf16 v[130:133], v[112:115], v[12:15], v[130:133]
	v_cvt_pk_bf16_f32 v18, v64, v65
	v_cvt_pk_bf16_f32 v19, v66, v67
	s_waitcnt lgkmcnt(4)
	v_mul_f32_e32 v36, v36, v92
	v_mul_f32_e32 v37, v37, v93
	v_mfma_f32_16x16x32_bf16 v[134:137], v[112:115], v[16:19], v[134:137]
	v_mul_f32_e32 v38, v38, v94
	v_mul_f32_e32 v39, v39, v95
	v_mul_f32_e32 v40, v40, v92
	v_mul_f32_e32 v41, v41, v93
	v_mul_f32_e32 v42, v42, v94
	v_mul_f32_e32 v43, v43, v95
	v_cvt_pk_bf16_f32 v84, v131, v116
	s_waitcnt lgkmcnt(2)
	v_mul_f32_e32 v44, v44, v96
	v_cvt_pk_bf16_f32 v88, v135, v117
	v_cndmask_b32_e64 v20, v130, v134, s[50:51]
	ds_write_b32 v25, v20 offset:768
	v_mfma_f32_16x16x32_bf16 v[36:39], v[68:71], v[84:87], v[36:39]
	v_mul_f32_e32 v45, v45, v97
	v_mul_f32_e32 v46, v46, v98
	v_mul_f32_e32 v47, v47, v99
	ds_read2_b64 v[108:111], v21 offset0:130 offset1:134
	v_mfma_f32_16x16x32_bf16 v[40:43], v[68:71], v[88:91], v[40:43]
	v_mul_f32_e32 v48, v48, v96
	v_mul_f32_e32 v49, v49, v97
	v_mul_f32_e32 v50, v50, v98
	v_mul_f32_e32 v51, v51, v99
	ds_read_b32 v68, v23 offset:8832
	v_mfma_f32_16x16x32_bf16 v[44:47], v[72:75], v[84:87], v[44:47]
	s_waitcnt lgkmcnt(4)
	v_mul_f32_e32 v52, v52, v100
	v_mul_f32_e32 v53, v53, v101
	v_mul_f32_e32 v54, v54, v102
	v_mul_f32_e32 v55, v55, v103
	ds_read2_b64 v[112:115], v21 offset0:138 offset1:142
	v_mfma_f32_16x16x32_bf16 v[48:51], v[72:75], v[88:91], v[48:51]
	v_mul_f32_e32 v56, v56, v100
	v_mul_f32_e32 v57, v57, v101
	v_mul_f32_e32 v58, v58, v102
	v_mul_f32_e32 v59, v59, v103
	ds_read_b32 v72, v23 offset:8896
	v_mfma_f32_16x16x32_bf16 v[52:55], v[76:79], v[84:87], v[52:55]
	s_waitcnt lgkmcnt(5)
	v_mul_f32_e32 v60, v60, v104
	v_mul_f32_e32 v61, v61, v105
	v_mul_f32_e32 v62, v62, v106
	v_mul_f32_e32 v63, v63, v107
	ds_read_b32 v116, v24 offset:8576
	v_mfma_f32_16x16x32_bf16 v[56:59], v[76:79], v[88:91], v[56:59]
	v_mul_f32_e32 v64, v64, v104
	v_mul_f32_e32 v65, v65, v105
	v_mul_f32_e32 v66, v66, v106
	v_mul_f32_e32 v67, v67, v107
	ds_read_b32 v76, v23 offset:8960
	v_mfma_f32_16x16x32_bf16 v[60:63], v[80:83], v[84:87], v[60:63]
	ds_read_b32 v117, v24 offset:8640
	ds_read_b128 v[92:95], v22 offset:8320
	v_add_u32_e32 v21, 0x820, v21
	v_mfma_f32_16x16x32_bf16 v[64:67], v[80:83], v[88:91], v[64:67]
	ds_read_b32 v80, v23 offset:9024
	ds_read_b128 v[96:99], v22 offset:8384
	v_cvt_pk_bf16_f32 v138, v36, v37
	v_cvt_pk_bf16_f32 v139, v38, v39
	v_cvt_pk_bf16_f32 v140, v44, v45
	v_cvt_pk_bf16_f32 v141, v46, v47
	ds_read_b128 v[100:103], v22 offset:8448
	v_cvt_pk_bf16_f32 v144, v40, v41
	v_cvt_pk_bf16_f32 v145, v42, v43
	s_waitcnt lgkmcnt(10)
	v_mfma_f32_16x16x32_bf16 v[130:133], v[108:111], v[138:141], 0
	v_cvt_pk_bf16_f32 v146, v48, v49
	v_cvt_pk_bf16_f32 v147, v50, v51
	ds_read_b128 v[104:107], v22 offset:8512
	v_cvt_pk_bf16_f32 v12, v52, v53
	v_cvt_pk_bf16_f32 v13, v54, v55
	v_mfma_f32_16x16x32_bf16 v[134:137], v[108:111], v[144:147], 0
	v_cvt_pk_bf16_f32 v14, v60, v61
	v_cvt_pk_bf16_f32 v15, v62, v63
	v_cvt_pk_bf16_f32 v16, v56, v57
	v_cvt_pk_bf16_f32 v17, v58, v59
	s_waitcnt lgkmcnt(9)
	v_mfma_f32_16x16x32_bf16 v[130:133], v[112:115], v[12:15], v[130:133]
	v_cvt_pk_bf16_f32 v18, v64, v65
	v_cvt_pk_bf16_f32 v19, v66, v67
	s_waitcnt lgkmcnt(4)
	v_mul_f32_e32 v36, v36, v92
	v_mul_f32_e32 v37, v37, v93
	v_mfma_f32_16x16x32_bf16 v[134:137], v[112:115], v[16:19], v[134:137]
	v_mul_f32_e32 v38, v38, v94
	v_mul_f32_e32 v39, v39, v95
	v_mul_f32_e32 v40, v40, v92
	v_mul_f32_e32 v41, v41, v93
	v_mul_f32_e32 v42, v42, v94
	v_mul_f32_e32 v43, v43, v95
	v_cvt_pk_bf16_f32 v84, v131, v116
	s_waitcnt lgkmcnt(2)
	v_mul_f32_e32 v44, v44, v96
	v_cvt_pk_bf16_f32 v88, v135, v117
	v_cndmask_b32_e64 v20, v130, v134, s[50:51]
	ds_write_b32 v25, v20 offset:896
	v_mfma_f32_16x16x32_bf16 v[36:39], v[68:71], v[84:87], v[36:39]
	v_mul_f32_e32 v45, v45, v97
	v_mul_f32_e32 v46, v46, v98
	v_mul_f32_e32 v47, v47, v99
	ds_read2_b64 v[108:111], v21 offset0:0 offset1:4
	v_mfma_f32_16x16x32_bf16 v[40:43], v[68:71], v[88:91], v[40:43]
	v_mul_f32_e32 v48, v48, v96
	v_mul_f32_e32 v49, v49, v97
	v_mul_f32_e32 v50, v50, v98
	v_mul_f32_e32 v51, v51, v99
	ds_read_b32 v68, v23 offset:9872
	v_mfma_f32_16x16x32_bf16 v[44:47], v[72:75], v[84:87], v[44:47]
	s_waitcnt lgkmcnt(4)
	v_mul_f32_e32 v52, v52, v100
	v_mul_f32_e32 v53, v53, v101
	v_mul_f32_e32 v54, v54, v102
	v_mul_f32_e32 v55, v55, v103
	ds_read2_b64 v[112:115], v21 offset0:8 offset1:12
	v_mfma_f32_16x16x32_bf16 v[48:51], v[72:75], v[88:91], v[48:51]
	v_mul_f32_e32 v56, v56, v100
	v_mul_f32_e32 v57, v57, v101
	v_mul_f32_e32 v58, v58, v102
	v_mul_f32_e32 v59, v59, v103
	ds_read_b32 v72, v23 offset:9936
	v_mfma_f32_16x16x32_bf16 v[52:55], v[76:79], v[84:87], v[52:55]
	s_waitcnt lgkmcnt(5)
	v_mul_f32_e32 v60, v60, v104
	v_mul_f32_e32 v61, v61, v105
	v_mul_f32_e32 v62, v62, v106
	v_mul_f32_e32 v63, v63, v107
	ds_read_b32 v116, v24 offset:9616
	v_mfma_f32_16x16x32_bf16 v[56:59], v[76:79], v[88:91], v[56:59]
	v_mul_f32_e32 v64, v64, v104
	v_mul_f32_e32 v65, v65, v105
	v_mul_f32_e32 v66, v66, v106
	v_mul_f32_e32 v67, v67, v107
	ds_read_b32 v76, v23 offset:10000
	v_mfma_f32_16x16x32_bf16 v[60:63], v[80:83], v[84:87], v[60:63]
	ds_read_b32 v117, v24 offset:9680
	ds_read_b128 v[92:95], v22 offset:9360
	v_mfma_f32_16x16x32_bf16 v[64:67], v[80:83], v[88:91], v[64:67]
	ds_read_b32 v80, v23 offset:10064
	ds_read_b128 v[96:99], v22 offset:9424
	v_cvt_pk_bf16_f32 v138, v36, v37
	v_cvt_pk_bf16_f32 v139, v38, v39
	v_cvt_pk_bf16_f32 v140, v44, v45
	v_cvt_pk_bf16_f32 v141, v46, v47
	ds_read_b128 v[100:103], v22 offset:9488
	v_cvt_pk_bf16_f32 v144, v40, v41
	v_cvt_pk_bf16_f32 v145, v42, v43
	s_waitcnt lgkmcnt(10)
	v_mfma_f32_16x16x32_bf16 v[130:133], v[108:111], v[138:141], 0
	v_cvt_pk_bf16_f32 v146, v48, v49
	v_cvt_pk_bf16_f32 v147, v50, v51
	ds_read_b128 v[104:107], v22 offset:9552
	v_cvt_pk_bf16_f32 v12, v52, v53
	v_cvt_pk_bf16_f32 v13, v54, v55
	v_mfma_f32_16x16x32_bf16 v[134:137], v[108:111], v[144:147], 0
	v_cvt_pk_bf16_f32 v14, v60, v61
	v_cvt_pk_bf16_f32 v15, v62, v63
	v_cvt_pk_bf16_f32 v16, v56, v57
	v_cvt_pk_bf16_f32 v17, v58, v59
	s_waitcnt lgkmcnt(9)
	v_mfma_f32_16x16x32_bf16 v[130:133], v[112:115], v[12:15], v[130:133]
	v_cvt_pk_bf16_f32 v18, v64, v65
	v_cvt_pk_bf16_f32 v19, v66, v67
	s_waitcnt lgkmcnt(4)
	v_mul_f32_e32 v36, v36, v92
	v_mul_f32_e32 v37, v37, v93
	v_mfma_f32_16x16x32_bf16 v[134:137], v[112:115], v[16:19], v[134:137]
	v_mul_f32_e32 v38, v38, v94
	v_mul_f32_e32 v39, v39, v95
	v_mul_f32_e32 v40, v40, v92
	v_mul_f32_e32 v41, v41, v93
	v_mul_f32_e32 v42, v42, v94
	v_mul_f32_e32 v43, v43, v95
	v_cvt_pk_bf16_f32 v84, v131, v116
	s_waitcnt lgkmcnt(2)
	v_mul_f32_e32 v44, v44, v96
	v_cvt_pk_bf16_f32 v88, v135, v117
	v_cndmask_b32_e64 v20, v130, v134, s[50:51]
	ds_write_b32 v25, v20 offset:1024
	v_mfma_f32_16x16x32_bf16 v[36:39], v[68:71], v[84:87], v[36:39]
	v_mul_f32_e32 v45, v45, v97
	v_mul_f32_e32 v46, v46, v98
	v_mul_f32_e32 v47, v47, v99
	ds_read2_b64 v[108:111], v21 offset0:130 offset1:134
	v_mfma_f32_16x16x32_bf16 v[40:43], v[68:71], v[88:91], v[40:43]
	v_mul_f32_e32 v48, v48, v96
	v_mul_f32_e32 v49, v49, v97
	v_mul_f32_e32 v50, v50, v98
	v_mul_f32_e32 v51, v51, v99
	ds_read_b32 v68, v23 offset:10912
	v_mfma_f32_16x16x32_bf16 v[44:47], v[72:75], v[84:87], v[44:47]
	s_waitcnt lgkmcnt(4)
	v_mul_f32_e32 v52, v52, v100
	v_mul_f32_e32 v53, v53, v101
	v_mul_f32_e32 v54, v54, v102
	v_mul_f32_e32 v55, v55, v103
	ds_read2_b64 v[112:115], v21 offset0:138 offset1:142
	v_mfma_f32_16x16x32_bf16 v[48:51], v[72:75], v[88:91], v[48:51]
	v_mul_f32_e32 v56, v56, v100
	v_mul_f32_e32 v57, v57, v101
	v_mul_f32_e32 v58, v58, v102
	v_mul_f32_e32 v59, v59, v103
	ds_read_b32 v72, v23 offset:10976
	v_mfma_f32_16x16x32_bf16 v[52:55], v[76:79], v[84:87], v[52:55]
	s_waitcnt lgkmcnt(5)
	v_mul_f32_e32 v60, v60, v104
	v_mul_f32_e32 v61, v61, v105
	v_mul_f32_e32 v62, v62, v106
	v_mul_f32_e32 v63, v63, v107
	ds_read_b32 v116, v24 offset:10656
	v_mfma_f32_16x16x32_bf16 v[56:59], v[76:79], v[88:91], v[56:59]
	v_mul_f32_e32 v64, v64, v104
	v_mul_f32_e32 v65, v65, v105
	v_mul_f32_e32 v66, v66, v106
	v_mul_f32_e32 v67, v67, v107
	ds_read_b32 v76, v23 offset:11040
	v_mfma_f32_16x16x32_bf16 v[60:63], v[80:83], v[84:87], v[60:63]
	ds_read_b32 v117, v24 offset:10720
	ds_read_b128 v[92:95], v22 offset:10400
	v_add_u32_e32 v21, 0x820, v21
	v_mfma_f32_16x16x32_bf16 v[64:67], v[80:83], v[88:91], v[64:67]
	ds_read_b32 v80, v23 offset:11104
	ds_read_b128 v[96:99], v22 offset:10464
	v_cvt_pk_bf16_f32 v138, v36, v37
	v_cvt_pk_bf16_f32 v139, v38, v39
	v_cvt_pk_bf16_f32 v140, v44, v45
	v_cvt_pk_bf16_f32 v141, v46, v47
	ds_read_b128 v[100:103], v22 offset:10528
	v_cvt_pk_bf16_f32 v144, v40, v41
	v_cvt_pk_bf16_f32 v145, v42, v43
	s_waitcnt lgkmcnt(10)
	v_mfma_f32_16x16x32_bf16 v[130:133], v[108:111], v[138:141], 0
	v_cvt_pk_bf16_f32 v146, v48, v49
	v_cvt_pk_bf16_f32 v147, v50, v51
	ds_read_b128 v[104:107], v22 offset:10592
	v_cvt_pk_bf16_f32 v12, v52, v53
	v_cvt_pk_bf16_f32 v13, v54, v55
	v_mfma_f32_16x16x32_bf16 v[134:137], v[108:111], v[144:147], 0
	v_cvt_pk_bf16_f32 v14, v60, v61
	v_cvt_pk_bf16_f32 v15, v62, v63
	v_cvt_pk_bf16_f32 v16, v56, v57
	v_cvt_pk_bf16_f32 v17, v58, v59
	s_waitcnt lgkmcnt(9)
	v_mfma_f32_16x16x32_bf16 v[130:133], v[112:115], v[12:15], v[130:133]
	v_cvt_pk_bf16_f32 v18, v64, v65
	v_cvt_pk_bf16_f32 v19, v66, v67
	s_waitcnt lgkmcnt(4)
	v_mul_f32_e32 v36, v36, v92
	v_mul_f32_e32 v37, v37, v93
	v_mfma_f32_16x16x32_bf16 v[134:137], v[112:115], v[16:19], v[134:137]
	v_mul_f32_e32 v38, v38, v94
	v_mul_f32_e32 v39, v39, v95
	v_mul_f32_e32 v40, v40, v92
	v_mul_f32_e32 v41, v41, v93
	v_mul_f32_e32 v42, v42, v94
	v_mul_f32_e32 v43, v43, v95
	v_cvt_pk_bf16_f32 v84, v131, v116
	s_waitcnt lgkmcnt(2)
	v_mul_f32_e32 v44, v44, v96
	v_cvt_pk_bf16_f32 v88, v135, v117
	v_cndmask_b32_e64 v20, v130, v134, s[50:51]
	ds_write_b32 v25, v20 offset:1152
	v_mfma_f32_16x16x32_bf16 v[36:39], v[68:71], v[84:87], v[36:39]
	v_mul_f32_e32 v45, v45, v97
	v_mul_f32_e32 v46, v46, v98
	v_mul_f32_e32 v47, v47, v99
	ds_read2_b64 v[108:111], v21 offset0:0 offset1:4
	v_mfma_f32_16x16x32_bf16 v[40:43], v[68:71], v[88:91], v[40:43]
	v_mul_f32_e32 v48, v48, v96
	v_mul_f32_e32 v49, v49, v97
	v_mul_f32_e32 v50, v50, v98
	v_mul_f32_e32 v51, v51, v99
	ds_read_b32 v68, v23 offset:11952
	v_mfma_f32_16x16x32_bf16 v[44:47], v[72:75], v[84:87], v[44:47]
	s_waitcnt lgkmcnt(4)
	v_mul_f32_e32 v52, v52, v100
	v_mul_f32_e32 v53, v53, v101
	v_mul_f32_e32 v54, v54, v102
	v_mul_f32_e32 v55, v55, v103
	ds_read2_b64 v[112:115], v21 offset0:8 offset1:12
	v_mfma_f32_16x16x32_bf16 v[48:51], v[72:75], v[88:91], v[48:51]
	v_mul_f32_e32 v56, v56, v100
	v_mul_f32_e32 v57, v57, v101
	v_mul_f32_e32 v58, v58, v102
	v_mul_f32_e32 v59, v59, v103
	ds_read_b32 v72, v23 offset:12016
	v_mfma_f32_16x16x32_bf16 v[52:55], v[76:79], v[84:87], v[52:55]
	s_waitcnt lgkmcnt(5)
	v_mul_f32_e32 v60, v60, v104
	v_mul_f32_e32 v61, v61, v105
	v_mul_f32_e32 v62, v62, v106
	v_mul_f32_e32 v63, v63, v107
	ds_read_b32 v116, v24 offset:11696
	v_mfma_f32_16x16x32_bf16 v[56:59], v[76:79], v[88:91], v[56:59]
	v_mul_f32_e32 v64, v64, v104
	v_mul_f32_e32 v65, v65, v105
	v_mul_f32_e32 v66, v66, v106
	v_mul_f32_e32 v67, v67, v107
	ds_read_b32 v76, v23 offset:12080
	v_mfma_f32_16x16x32_bf16 v[60:63], v[80:83], v[84:87], v[60:63]
	ds_read_b32 v117, v24 offset:11760
	ds_read_b128 v[92:95], v22 offset:11440
	v_mfma_f32_16x16x32_bf16 v[64:67], v[80:83], v[88:91], v[64:67]
	ds_read_b32 v80, v23 offset:12144
	ds_read_b128 v[96:99], v22 offset:11504
	v_cvt_pk_bf16_f32 v138, v36, v37
	v_cvt_pk_bf16_f32 v139, v38, v39
	v_cvt_pk_bf16_f32 v140, v44, v45
	v_cvt_pk_bf16_f32 v141, v46, v47
	ds_read_b128 v[100:103], v22 offset:11568
	v_cvt_pk_bf16_f32 v144, v40, v41
	v_cvt_pk_bf16_f32 v145, v42, v43
	s_waitcnt lgkmcnt(10)
	v_mfma_f32_16x16x32_bf16 v[130:133], v[108:111], v[138:141], 0
	v_cvt_pk_bf16_f32 v146, v48, v49
	v_cvt_pk_bf16_f32 v147, v50, v51
	ds_read_b128 v[104:107], v22 offset:11632
	v_cvt_pk_bf16_f32 v12, v52, v53
	v_cvt_pk_bf16_f32 v13, v54, v55
	v_mfma_f32_16x16x32_bf16 v[134:137], v[108:111], v[144:147], 0
	v_cvt_pk_bf16_f32 v14, v60, v61
	v_cvt_pk_bf16_f32 v15, v62, v63
	v_cvt_pk_bf16_f32 v16, v56, v57
	v_cvt_pk_bf16_f32 v17, v58, v59
	s_waitcnt lgkmcnt(9)
	v_mfma_f32_16x16x32_bf16 v[130:133], v[112:115], v[12:15], v[130:133]
	v_cvt_pk_bf16_f32 v18, v64, v65
	v_cvt_pk_bf16_f32 v19, v66, v67
	s_waitcnt lgkmcnt(4)
	v_mul_f32_e32 v36, v36, v92
	v_mul_f32_e32 v37, v37, v93
	v_mfma_f32_16x16x32_bf16 v[134:137], v[112:115], v[16:19], v[134:137]
	v_mul_f32_e32 v38, v38, v94
	v_mul_f32_e32 v39, v39, v95
	v_mul_f32_e32 v40, v40, v92
	v_mul_f32_e32 v41, v41, v93
	v_mul_f32_e32 v42, v42, v94
	v_mul_f32_e32 v43, v43, v95
	v_cvt_pk_bf16_f32 v84, v131, v116
	s_waitcnt lgkmcnt(2)
	v_mul_f32_e32 v44, v44, v96
	v_cvt_pk_bf16_f32 v88, v135, v117
	v_cndmask_b32_e64 v20, v130, v134, s[50:51]
	ds_write_b32 v25, v20 offset:1280
	v_mfma_f32_16x16x32_bf16 v[36:39], v[68:71], v[84:87], v[36:39]
	v_mul_f32_e32 v45, v45, v97
	v_mul_f32_e32 v46, v46, v98
	v_mul_f32_e32 v47, v47, v99
	ds_read2_b64 v[108:111], v21 offset0:130 offset1:134
	v_mfma_f32_16x16x32_bf16 v[40:43], v[68:71], v[88:91], v[40:43]
	v_mul_f32_e32 v48, v48, v96
	v_mul_f32_e32 v49, v49, v97
	v_mul_f32_e32 v50, v50, v98
	v_mul_f32_e32 v51, v51, v99
	ds_read_b32 v68, v23 offset:12992
	v_mfma_f32_16x16x32_bf16 v[44:47], v[72:75], v[84:87], v[44:47]
	s_waitcnt lgkmcnt(4)
	v_mul_f32_e32 v52, v52, v100
	v_mul_f32_e32 v53, v53, v101
	v_mul_f32_e32 v54, v54, v102
	v_mul_f32_e32 v55, v55, v103
	ds_read2_b64 v[112:115], v21 offset0:138 offset1:142
	v_mfma_f32_16x16x32_bf16 v[48:51], v[72:75], v[88:91], v[48:51]
	v_mul_f32_e32 v56, v56, v100
	v_mul_f32_e32 v57, v57, v101
	v_mul_f32_e32 v58, v58, v102
	v_mul_f32_e32 v59, v59, v103
	ds_read_b32 v72, v23 offset:13056
	v_mfma_f32_16x16x32_bf16 v[52:55], v[76:79], v[84:87], v[52:55]
	s_waitcnt lgkmcnt(5)
	v_mul_f32_e32 v60, v60, v104
	v_mul_f32_e32 v61, v61, v105
	v_mul_f32_e32 v62, v62, v106
	v_mul_f32_e32 v63, v63, v107
	ds_read_b32 v116, v24 offset:12736
	v_mfma_f32_16x16x32_bf16 v[56:59], v[76:79], v[88:91], v[56:59]
	v_mul_f32_e32 v64, v64, v104
	v_mul_f32_e32 v65, v65, v105
	v_mul_f32_e32 v66, v66, v106
	v_mul_f32_e32 v67, v67, v107
	ds_read_b32 v76, v23 offset:13120
	v_mfma_f32_16x16x32_bf16 v[60:63], v[80:83], v[84:87], v[60:63]
	ds_read_b32 v117, v24 offset:12800
	ds_read_b128 v[92:95], v22 offset:12480
	v_add_u32_e32 v21, 0x820, v21
	v_mfma_f32_16x16x32_bf16 v[64:67], v[80:83], v[88:91], v[64:67]
	ds_read_b32 v80, v23 offset:13184
	ds_read_b128 v[96:99], v22 offset:12544
	v_cvt_pk_bf16_f32 v138, v36, v37
	v_cvt_pk_bf16_f32 v139, v38, v39
	v_cvt_pk_bf16_f32 v140, v44, v45
	v_cvt_pk_bf16_f32 v141, v46, v47
	ds_read_b128 v[100:103], v22 offset:12608
	v_cvt_pk_bf16_f32 v144, v40, v41
	v_cvt_pk_bf16_f32 v145, v42, v43
	s_waitcnt lgkmcnt(10)
	v_mfma_f32_16x16x32_bf16 v[130:133], v[108:111], v[138:141], 0
	v_cvt_pk_bf16_f32 v146, v48, v49
	v_cvt_pk_bf16_f32 v147, v50, v51
	ds_read_b128 v[104:107], v22 offset:12672
	v_cvt_pk_bf16_f32 v12, v52, v53
	v_cvt_pk_bf16_f32 v13, v54, v55
	v_mfma_f32_16x16x32_bf16 v[134:137], v[108:111], v[144:147], 0
	v_cvt_pk_bf16_f32 v14, v60, v61
	v_cvt_pk_bf16_f32 v15, v62, v63
	v_cvt_pk_bf16_f32 v16, v56, v57
	v_cvt_pk_bf16_f32 v17, v58, v59
	s_waitcnt lgkmcnt(9)
	v_mfma_f32_16x16x32_bf16 v[130:133], v[112:115], v[12:15], v[130:133]
	v_cvt_pk_bf16_f32 v18, v64, v65
	v_cvt_pk_bf16_f32 v19, v66, v67
	s_waitcnt lgkmcnt(4)
	v_mul_f32_e32 v36, v36, v92
	v_mul_f32_e32 v37, v37, v93
	v_mfma_f32_16x16x32_bf16 v[134:137], v[112:115], v[16:19], v[134:137]
	v_mul_f32_e32 v38, v38, v94
	v_mul_f32_e32 v39, v39, v95
	v_mul_f32_e32 v40, v40, v92
	v_mul_f32_e32 v41, v41, v93
	v_mul_f32_e32 v42, v42, v94
	v_mul_f32_e32 v43, v43, v95
	v_cvt_pk_bf16_f32 v84, v131, v116
	s_waitcnt lgkmcnt(2)
	v_mul_f32_e32 v44, v44, v96
	v_cvt_pk_bf16_f32 v88, v135, v117
	v_cndmask_b32_e64 v20, v130, v134, s[50:51]
	ds_write_b32 v25, v20 offset:1408
	v_mfma_f32_16x16x32_bf16 v[36:39], v[68:71], v[84:87], v[36:39]
	v_mul_f32_e32 v45, v45, v97
	v_mul_f32_e32 v46, v46, v98
	v_mul_f32_e32 v47, v47, v99
	ds_read2_b64 v[108:111], v21 offset0:0 offset1:4
	v_mfma_f32_16x16x32_bf16 v[40:43], v[68:71], v[88:91], v[40:43]
	v_mul_f32_e32 v48, v48, v96
	v_mul_f32_e32 v49, v49, v97
	v_mul_f32_e32 v50, v50, v98
	v_mul_f32_e32 v51, v51, v99
	ds_read_b32 v68, v23 offset:14032
	v_mfma_f32_16x16x32_bf16 v[44:47], v[72:75], v[84:87], v[44:47]
	s_waitcnt lgkmcnt(4)
	v_mul_f32_e32 v52, v52, v100
	v_mul_f32_e32 v53, v53, v101
	v_mul_f32_e32 v54, v54, v102
	v_mul_f32_e32 v55, v55, v103
	ds_read2_b64 v[112:115], v21 offset0:8 offset1:12
	v_mfma_f32_16x16x32_bf16 v[48:51], v[72:75], v[88:91], v[48:51]
	v_mul_f32_e32 v56, v56, v100
	v_mul_f32_e32 v57, v57, v101
	v_mul_f32_e32 v58, v58, v102
	v_mul_f32_e32 v59, v59, v103
	ds_read_b32 v72, v23 offset:14096
	v_mfma_f32_16x16x32_bf16 v[52:55], v[76:79], v[84:87], v[52:55]
	s_waitcnt lgkmcnt(5)
	v_mul_f32_e32 v60, v60, v104
	v_mul_f32_e32 v61, v61, v105
	v_mul_f32_e32 v62, v62, v106
	v_mul_f32_e32 v63, v63, v107
	ds_read_b32 v116, v24 offset:13776
	v_mfma_f32_16x16x32_bf16 v[56:59], v[76:79], v[88:91], v[56:59]
	v_mul_f32_e32 v64, v64, v104
	v_mul_f32_e32 v65, v65, v105
	v_mul_f32_e32 v66, v66, v106
	v_mul_f32_e32 v67, v67, v107
	ds_read_b32 v76, v23 offset:14160
	v_mfma_f32_16x16x32_bf16 v[60:63], v[80:83], v[84:87], v[60:63]
	ds_read_b32 v117, v24 offset:13840
	ds_read_b128 v[92:95], v22 offset:13520
	v_mfma_f32_16x16x32_bf16 v[64:67], v[80:83], v[88:91], v[64:67]
	ds_read_b32 v80, v23 offset:14224
	ds_read_b128 v[96:99], v22 offset:13584
	v_cvt_pk_bf16_f32 v138, v36, v37
	v_cvt_pk_bf16_f32 v139, v38, v39
	v_cvt_pk_bf16_f32 v140, v44, v45
	v_cvt_pk_bf16_f32 v141, v46, v47
	ds_read_b128 v[100:103], v22 offset:13648
	v_cvt_pk_bf16_f32 v144, v40, v41
	v_cvt_pk_bf16_f32 v145, v42, v43
	s_waitcnt lgkmcnt(10)
	v_mfma_f32_16x16x32_bf16 v[130:133], v[108:111], v[138:141], 0
	v_cvt_pk_bf16_f32 v146, v48, v49
	v_cvt_pk_bf16_f32 v147, v50, v51
	ds_read_b128 v[104:107], v22 offset:13712
	v_cvt_pk_bf16_f32 v12, v52, v53
	v_cvt_pk_bf16_f32 v13, v54, v55
	v_mfma_f32_16x16x32_bf16 v[134:137], v[108:111], v[144:147], 0
	v_cvt_pk_bf16_f32 v14, v60, v61
	v_cvt_pk_bf16_f32 v15, v62, v63
	v_cvt_pk_bf16_f32 v16, v56, v57
	v_cvt_pk_bf16_f32 v17, v58, v59
	s_waitcnt lgkmcnt(9)
	v_mfma_f32_16x16x32_bf16 v[130:133], v[112:115], v[12:15], v[130:133]
	v_cvt_pk_bf16_f32 v18, v64, v65
	v_cvt_pk_bf16_f32 v19, v66, v67
	s_waitcnt lgkmcnt(4)
	v_mul_f32_e32 v36, v36, v92
	v_mul_f32_e32 v37, v37, v93
	v_mfma_f32_16x16x32_bf16 v[134:137], v[112:115], v[16:19], v[134:137]
	v_mul_f32_e32 v38, v38, v94
	v_mul_f32_e32 v39, v39, v95
	v_mul_f32_e32 v40, v40, v92
	v_mul_f32_e32 v41, v41, v93
	v_mul_f32_e32 v42, v42, v94
	v_mul_f32_e32 v43, v43, v95
	v_cvt_pk_bf16_f32 v84, v131, v116
	s_waitcnt lgkmcnt(2)
	v_mul_f32_e32 v44, v44, v96
	v_cvt_pk_bf16_f32 v88, v135, v117
	v_cndmask_b32_e64 v20, v130, v134, s[50:51]
	ds_write_b32 v25, v20 offset:1536
	v_mfma_f32_16x16x32_bf16 v[36:39], v[68:71], v[84:87], v[36:39]
	v_mul_f32_e32 v45, v45, v97
	v_mul_f32_e32 v46, v46, v98
	v_mul_f32_e32 v47, v47, v99
	ds_read2_b64 v[108:111], v21 offset0:130 offset1:134
	v_mfma_f32_16x16x32_bf16 v[40:43], v[68:71], v[88:91], v[40:43]
	v_mul_f32_e32 v48, v48, v96
	v_mul_f32_e32 v49, v49, v97
	v_mul_f32_e32 v50, v50, v98
	v_mul_f32_e32 v51, v51, v99
	ds_read_b32 v68, v23 offset:15072
	v_mfma_f32_16x16x32_bf16 v[44:47], v[72:75], v[84:87], v[44:47]
	s_waitcnt lgkmcnt(4)
	v_mul_f32_e32 v52, v52, v100
	v_mul_f32_e32 v53, v53, v101
	v_mul_f32_e32 v54, v54, v102
	v_mul_f32_e32 v55, v55, v103
	ds_read2_b64 v[112:115], v21 offset0:138 offset1:142
	v_mfma_f32_16x16x32_bf16 v[48:51], v[72:75], v[88:91], v[48:51]
	v_mul_f32_e32 v56, v56, v100
	v_mul_f32_e32 v57, v57, v101
	v_mul_f32_e32 v58, v58, v102
	v_mul_f32_e32 v59, v59, v103
	ds_read_b32 v72, v23 offset:15136
	v_mfma_f32_16x16x32_bf16 v[52:55], v[76:79], v[84:87], v[52:55]
	s_waitcnt lgkmcnt(5)
	v_mul_f32_e32 v60, v60, v104
	v_mul_f32_e32 v61, v61, v105
	v_mul_f32_e32 v62, v62, v106
	v_mul_f32_e32 v63, v63, v107
	ds_read_b32 v116, v24 offset:14816
	v_mfma_f32_16x16x32_bf16 v[56:59], v[76:79], v[88:91], v[56:59]
	v_mul_f32_e32 v64, v64, v104
	v_mul_f32_e32 v65, v65, v105
	v_mul_f32_e32 v66, v66, v106
	v_mul_f32_e32 v67, v67, v107
	ds_read_b32 v76, v23 offset:15200
	v_mfma_f32_16x16x32_bf16 v[60:63], v[80:83], v[84:87], v[60:63]
	ds_read_b32 v117, v24 offset:14880
	ds_read_b128 v[92:95], v22 offset:14560
	v_add_u32_e32 v21, 0x820, v21
	v_mfma_f32_16x16x32_bf16 v[64:67], v[80:83], v[88:91], v[64:67]
	ds_read_b32 v80, v23 offset:15264
	ds_read_b128 v[96:99], v22 offset:14624
	v_cvt_pk_bf16_f32 v138, v36, v37
	v_cvt_pk_bf16_f32 v139, v38, v39
	v_cvt_pk_bf16_f32 v140, v44, v45
	v_cvt_pk_bf16_f32 v141, v46, v47
	ds_read_b128 v[100:103], v22 offset:14688
	v_cvt_pk_bf16_f32 v144, v40, v41
	v_cvt_pk_bf16_f32 v145, v42, v43
	s_waitcnt lgkmcnt(10)
	v_mfma_f32_16x16x32_bf16 v[130:133], v[108:111], v[138:141], 0
	v_cvt_pk_bf16_f32 v146, v48, v49
	v_cvt_pk_bf16_f32 v147, v50, v51
	ds_read_b128 v[104:107], v22 offset:14752
	v_cvt_pk_bf16_f32 v12, v52, v53
	v_cvt_pk_bf16_f32 v13, v54, v55
	v_mfma_f32_16x16x32_bf16 v[134:137], v[108:111], v[144:147], 0
	v_cvt_pk_bf16_f32 v14, v60, v61
	v_cvt_pk_bf16_f32 v15, v62, v63
	v_cvt_pk_bf16_f32 v16, v56, v57
	v_cvt_pk_bf16_f32 v17, v58, v59
	s_waitcnt lgkmcnt(9)
	v_mfma_f32_16x16x32_bf16 v[130:133], v[112:115], v[12:15], v[130:133]
	v_cvt_pk_bf16_f32 v18, v64, v65
	v_cvt_pk_bf16_f32 v19, v66, v67
	s_waitcnt lgkmcnt(4)
	v_mul_f32_e32 v36, v36, v92
	v_mul_f32_e32 v37, v37, v93
	v_mfma_f32_16x16x32_bf16 v[134:137], v[112:115], v[16:19], v[134:137]
	v_mul_f32_e32 v38, v38, v94
	v_mul_f32_e32 v39, v39, v95
	v_mul_f32_e32 v40, v40, v92
	v_mul_f32_e32 v41, v41, v93
	v_mul_f32_e32 v42, v42, v94
	v_mul_f32_e32 v43, v43, v95
	v_cvt_pk_bf16_f32 v84, v131, v116
	s_waitcnt lgkmcnt(2)
; __device__ __forceinline__ void scan_chunk(f32x4 (&c)[4][2], const LAS float* sl  , int rh, LAS float* ybuf  , int lane) {
;     ...
; #pragma unroll 1
;     for (int s = 0; s < CHS; s += 2) {
;         SCAN_STEP(s, wA, bkA, wB, bkB);
;         SCAN_STEP(s + 1, wB, bkB, wA, bkA);
;     }
	v_mul_f32_e32 v44, v44, v96
	v_cvt_pk_bf16_f32 v88, v135, v117
	v_cndmask_b32_e64 v20, v130, v134, s[50:51]
	ds_write_b32 v25, v20 offset:1664
	v_mfma_f32_16x16x32_bf16 v[36:39], v[68:71], v[84:87], v[36:39]
	v_mul_f32_e32 v45, v45, v97
	v_mul_f32_e32 v46, v46, v98
	v_mul_f32_e32 v47, v47, v99
	ds_read2_b64 v[108:111], v21 offset0:0 offset1:4
	v_mfma_f32_16x16x32_bf16 v[40:43], v[68:71], v[88:91], v[40:43]
	v_mul_f32_e32 v48, v48, v96
	v_mul_f32_e32 v49, v49, v97
	v_mul_f32_e32 v50, v50, v98
	v_mul_f32_e32 v51, v51, v99
	ds_read_b32 v68, v23 offset:16112
	v_mfma_f32_16x16x32_bf16 v[44:47], v[72:75], v[84:87], v[44:47]
	s_waitcnt lgkmcnt(4)
	v_mul_f32_e32 v52, v52, v100
	v_mul_f32_e32 v53, v53, v101
	v_mul_f32_e32 v54, v54, v102
	v_mul_f32_e32 v55, v55, v103
	ds_read2_b64 v[112:115], v21 offset0:8 offset1:12
	v_mfma_f32_16x16x32_bf16 v[48:51], v[72:75], v[88:91], v[48:51]
	v_mul_f32_e32 v56, v56, v100
	v_mul_f32_e32 v57, v57, v101
	v_mul_f32_e32 v58, v58, v102
	v_mul_f32_e32 v59, v59, v103
	ds_read_b32 v72, v23 offset:16176
	v_mfma_f32_16x16x32_bf16 v[52:55], v[76:79], v[84:87], v[52:55]
	s_waitcnt lgkmcnt(5)
	v_mul_f32_e32 v60, v60, v104
	v_mul_f32_e32 v61, v61, v105
	v_mul_f32_e32 v62, v62, v106
	v_mul_f32_e32 v63, v63, v107
	ds_read_b32 v116, v24 offset:15856
	v_mfma_f32_16x16x32_bf16 v[56:59], v[76:79], v[88:91], v[56:59]
	v_mul_f32_e32 v64, v64, v104
	v_mul_f32_e32 v65, v65, v105
	v_mul_f32_e32 v66, v66, v106
	v_mul_f32_e32 v67, v67, v107
	ds_read_b32 v76, v23 offset:16240
	v_mfma_f32_16x16x32_bf16 v[60:63], v[80:83], v[84:87], v[60:63]
	ds_read_b32 v117, v24 offset:15920
	ds_read_b128 v[92:95], v22 offset:15600
	v_mfma_f32_16x16x32_bf16 v[64:67], v[80:83], v[88:91], v[64:67]
	ds_read_b32 v80, v23 offset:16304
	ds_read_b128 v[96:99], v22 offset:15664
	v_cvt_pk_bf16_f32 v138, v36, v37
	v_cvt_pk_bf16_f32 v139, v38, v39
	v_cvt_pk_bf16_f32 v140, v44, v45
	v_cvt_pk_bf16_f32 v141, v46, v47
	ds_read_b128 v[100:103], v22 offset:15728
	v_cvt_pk_bf16_f32 v144, v40, v41
	v_cvt_pk_bf16_f32 v145, v42, v43
	s_waitcnt lgkmcnt(10)
	v_mfma_f32_16x16x32_bf16 v[130:133], v[108:111], v[138:141], 0
	v_cvt_pk_bf16_f32 v146, v48, v49
	v_cvt_pk_bf16_f32 v147, v50, v51
	ds_read_b128 v[104:107], v22 offset:15792
	v_cvt_pk_bf16_f32 v12, v52, v53
	v_cvt_pk_bf16_f32 v13, v54, v55
	v_mfma_f32_16x16x32_bf16 v[134:137], v[108:111], v[144:147], 0
	v_cvt_pk_bf16_f32 v14, v60, v61
	v_cvt_pk_bf16_f32 v15, v62, v63
	v_cvt_pk_bf16_f32 v16, v56, v57
	v_cvt_pk_bf16_f32 v17, v58, v59
	s_waitcnt lgkmcnt(9)
	v_mfma_f32_16x16x32_bf16 v[130:133], v[112:115], v[12:15], v[130:133]
	v_cvt_pk_bf16_f32 v18, v64, v65
	v_cvt_pk_bf16_f32 v19, v66, v67
	s_waitcnt lgkmcnt(4)
	v_mul_f32_e32 v36, v36, v92
	v_mul_f32_e32 v37, v37, v93
	v_mfma_f32_16x16x32_bf16 v[134:137], v[112:115], v[16:19], v[134:137]
	v_mul_f32_e32 v38, v38, v94
	v_mul_f32_e32 v39, v39, v95
	v_mul_f32_e32 v40, v40, v92
	v_mul_f32_e32 v41, v41, v93
	v_mul_f32_e32 v42, v42, v94
	v_mul_f32_e32 v43, v43, v95
	v_cvt_pk_bf16_f32 v84, v131, v116
	s_waitcnt lgkmcnt(2)
	v_mul_f32_e32 v44, v44, v96
	v_cvt_pk_bf16_f32 v88, v135, v117
	v_cndmask_b32_e64 v20, v130, v134, s[50:51]
	ds_write_b32 v25, v20 offset:1792
	v_mfma_f32_16x16x32_bf16 v[36:39], v[68:71], v[84:87], v[36:39]
	v_mul_f32_e32 v45, v45, v97
	v_mul_f32_e32 v46, v46, v98
	v_mul_f32_e32 v47, v47, v99
	ds_read2_b64 v[108:111], v21 offset0:130 offset1:134
	v_mfma_f32_16x16x32_bf16 v[40:43], v[68:71], v[88:91], v[40:43]
	v_mul_f32_e32 v48, v48, v96
	v_mul_f32_e32 v49, v49, v97
	v_mul_f32_e32 v50, v50, v98
	v_mul_f32_e32 v51, v51, v99
	v_mfma_f32_16x16x32_bf16 v[44:47], v[72:75], v[84:87], v[44:47]
	s_waitcnt lgkmcnt(3)
	v_mul_f32_e32 v52, v52, v100
	v_mul_f32_e32 v53, v53, v101
	v_mul_f32_e32 v54, v54, v102
	v_mul_f32_e32 v55, v55, v103
	ds_read2_b64 v[112:115], v21 offset0:138 offset1:142
	v_mfma_f32_16x16x32_bf16 v[48:51], v[72:75], v[88:91], v[48:51]
	v_mul_f32_e32 v56, v56, v100
	v_mul_f32_e32 v57, v57, v101
	v_mul_f32_e32 v58, v58, v102
	v_mul_f32_e32 v59, v59, v103
	v_mfma_f32_16x16x32_bf16 v[52:55], v[76:79], v[84:87], v[52:55]
	s_waitcnt lgkmcnt(3)
	v_mul_f32_e32 v60, v60, v104
	v_mul_f32_e32 v61, v61, v105
	v_mul_f32_e32 v62, v62, v106
	v_mul_f32_e32 v63, v63, v107
	v_mfma_f32_16x16x32_bf16 v[56:59], v[76:79], v[88:91], v[56:59]
	v_mul_f32_e32 v64, v64, v104
	v_mul_f32_e32 v65, v65, v105
	v_mul_f32_e32 v66, v66, v106
	v_mul_f32_e32 v67, v67, v107
	v_mfma_f32_16x16x32_bf16 v[60:63], v[80:83], v[84:87], v[60:63]
	s_nop 0
	v_mfma_f32_16x16x32_bf16 v[64:67], v[80:83], v[88:91], v[64:67]
	v_cvt_pk_bf16_f32 v138, v36, v37
	v_cvt_pk_bf16_f32 v139, v38, v39
	v_cvt_pk_bf16_f32 v140, v44, v45
	v_cvt_pk_bf16_f32 v141, v46, v47
	v_cvt_pk_bf16_f32 v144, v40, v41
	v_cvt_pk_bf16_f32 v145, v42, v43
	s_waitcnt lgkmcnt(1)
	v_mfma_f32_16x16x32_bf16 v[130:133], v[108:111], v[138:141], 0
	v_cvt_pk_bf16_f32 v146, v48, v49
	v_cvt_pk_bf16_f32 v147, v50, v51
	v_cvt_pk_bf16_f32 v12, v52, v53
	v_cvt_pk_bf16_f32 v13, v54, v55
	v_mfma_f32_16x16x32_bf16 v[134:137], v[108:111], v[144:147], 0
	v_cvt_pk_bf16_f32 v14, v60, v61
	v_cvt_pk_bf16_f32 v15, v62, v63
	v_cvt_pk_bf16_f32 v16, v56, v57
	v_cvt_pk_bf16_f32 v17, v58, v59
	s_waitcnt lgkmcnt(0)
	v_mfma_f32_16x16x32_bf16 v[130:133], v[112:115], v[12:15], v[130:133]
	v_cvt_pk_bf16_f32 v18, v64, v65
	v_cvt_pk_bf16_f32 v19, v66, v67
	s_nop 1
	v_mfma_f32_16x16x32_bf16 v[134:137], v[112:115], v[16:19], v[134:137]
	s_nop 7
	v_cndmask_b32_e64 v20, v130, v134, s[50:51]
	ds_write_b32 v25, v20 offset:1920
	s_branch .LBB0_435

; #define LDS_WAIT() asm volatile("s_waitcnt lgkmcnt(0)" ::: "memory")
; #define VM_WAIT() asm volatile("s_waitcnt vmcnt(0)" ::: "memory")
; __device__ __forceinline__ void scan_phase(int l, LAS unsigned char* lds, int wave, int lane) {
;     ...
;             if (c == NCH / 2) VM_WAIT(); else asm volatile("s_waitcnt vmcnt(4)" ::: "memory");
;             LDS_WAIT(); __syncthreads();
;         }
;         if (wave >= 4) { unsigned yo[4]; yflush_issue(yo, yb2, dirw, NCH - 1, lane); yflush_finish(yo, yb2, ybw + ((NCH - 1) & 1) * CHS * 32, dirw, NCH - 1, lane); }
;         VM_WAIT(); __syncthreads();
; __device__ __forceinline__ void xcd_barrier(const XcdBarrier& b) {
;     asm volatile("s_waitcnt vmcnt(0)" ::: "memory");
;     __syncthreads();
;     if (threadIdx.x == 0) {
;         unsigned* bar = b.bar;
;         __builtin_amdgcn_s_waitcnt(0);
;         unsigned nloc = b.st[0], nx = b.st[1];
;         if (nloc == 0u) { xcd_barrier_complete(bar, b.x, nloc, nx); b.st[0] = nloc; b.st[1] = nx; }
.LBB0_442:
	s_setprio 0
	s_waitcnt vmcnt(0)
	s_barrier
	s_and_saveexec_b64 s[30:31], s[56:57]
	s_cbranch_execz .LBB0_494
	s_add_i32 s26, 0, 0x26000
	v_mov_b32_e32 v2, s26
	s_waitcnt vmcnt(0) expcnt(0) lgkmcnt(0)
	ds_read_b32 v5, v2
	v_readlane_b32 s6, v254, 19
	s_waitcnt lgkmcnt(0)
	v_cmp_ne_u32_e32 vcc, 0, v5
	v_mov_b32_e32 v2, s6
	ds_read_b32 v4, v2
	s_cbranch_vccnz .LBB0_458
	s_mov_b32 s27, 1
	s_branch .LBB0_446
